# phase D: counted waits on the five activation sources; partial 2/3 and the first two weight batches issued while earlier sources are still being added
# speedup vs baseline: 1.0056x; 1.0056x over previous
; __global__ void __launch_bounds__(512, 2) hybrid_fwd(Params P) {
;     ...
;             for (int row = gwave; row < 8192; row += nwaves) { const int kv = row >> 12, rr = row & 4095, bg = rr >> 9, n = rr & 511;
;                 f32x4 hv = *(const f32x4*)((const float*)(ws + WS_SMALL) + kv * 256 + 4 * lane);
;                 { const float* pp = (const float*)(ws + WS_H) + ((size_t)(kv * 4) * 4096 + rr) * 256 + 4 * lane;
; #pragma unroll
;                     for (int ks = 0; ks < 4; ++ks) hv += *(const f32x4*)(pp + (size_t)ks * 4096 * 256);
.LBB0_777:
	s_or_b64 exec, exec, s[4:5]
	v_readlane_b32 s4, v255, 17
	s_mov_b32 s6, s4
	s_mov_b64 s[4:5], s[58:59]
	s_mov_b32 s14, s69
	s_mov_b32 s15, s2
	v_mov_b32_e32 v0, v146
	s_barrier
	v_readfirstlane_b32 s7, v0
	s_lshr_b32 s7, s7, 6
	s_cmp_gt_u32 s7, 1
	s_cbranch_scc1 .LBB0_784
	s_load_dwordx2 s[10:11], s[0:1], 0x50
	s_load_dwordx2 s[12:13], s[0:1], 0x38
	s_lshl_b32 s8, s15, 1
	s_add_u32 s8, s8, s7
	s_lshr_b32 s9, s8, 8
	s_and_b32 s8, s8, 0xff
	s_lshl_b32 s8, s8, 4
	v_and_b32_e32 v244, 63, v0
	v_and_b32_e32 v245, 15, v244
	v_lshrrev_b32_e32 v246, 4, v244
	v_lshlrev_b32_e32 v248, 8, v246
	v_lshl_add_u32 v247, v245, 10, v248
	v_lshlrev_b32_e32 v250, 4, v245
	v_lshl_add_u32 v249, v246, 14, v250
	v_lshlrev_b32_e32 v251, 3, v245
	v_lshl_add_u32 v251, v246, 9, v251
	v_lshlrev_b32_e32 v252, 3, v246
	v_lshl_add_u32 v252, v245, 12, v252
	s_lshl_b32 s16, s9, 10
	s_add_u32 s16, s16, 0x2400000
	s_add_u32 s98, s4, s16
	s_addc_u32 s99, s5, 0
	s_lshl_b32 s16, s9, 24
	s_lshl_b32 s18, s8, 10
	s_add_u32 s16, s16, s18
	s_add_u32 s16, s16, 0x3100000
	s_add_u32 s14, s4, s16
	s_addc_u32 s15, s5, 0
	s_waitcnt lgkmcnt(0)
	s_lshl_b32 s16, s6, 17
	s_lshl_b32 s18, s9, 16
	s_add_u32 s16, s16, s18
	s_add_u32 s10, s10, s16
	s_addc_u32 s11, s11, 0
	s_mul_i32 s16, s6, 0x300
	s_add_u32 s12, s12, s16
	s_addc_u32 s13, s13, 0
	global_load_dwordx4 v[240:243], v250, s[12:13]
	global_load_dwordx4 v[0:3], v248, s[98:99]
	global_load_dwordx4 v[4:7], v248, s[98:99] offset:16
	global_load_dwordx4 v[8:11], v248, s[98:99] offset:32
	global_load_dwordx4 v[12:15], v248, s[98:99] offset:48
	global_load_dwordx4 v[16:19], v248, s[98:99] offset:64
	global_load_dwordx4 v[20:23], v248, s[98:99] offset:80
	global_load_dwordx4 v[24:27], v248, s[98:99] offset:96
	global_load_dwordx4 v[28:31], v248, s[98:99] offset:112
	global_load_dwordx4 v[32:35], v248, s[98:99] offset:128
	global_load_dwordx4 v[36:39], v248, s[98:99] offset:144
	global_load_dwordx4 v[40:43], v248, s[98:99] offset:160
	global_load_dwordx4 v[44:47], v248, s[98:99] offset:176
	global_load_dwordx4 v[48:51], v248, s[98:99] offset:192
	global_load_dwordx4 v[52:55], v248, s[98:99] offset:208
	global_load_dwordx4 v[56:59], v248, s[98:99] offset:224
	global_load_dwordx4 v[60:63], v248, s[98:99] offset:240
	global_load_dwordx4 v[82:85], v247, s[14:15]
	global_load_dwordx4 v[86:89], v247, s[14:15] offset:16
	global_load_dwordx4 v[90:93], v247, s[14:15] offset:32
	global_load_dwordx4 v[94:97], v247, s[14:15] offset:48
	global_load_dwordx4 v[98:101], v247, s[14:15] offset:64
	global_load_dwordx4 v[102:105], v247, s[14:15] offset:80
	global_load_dwordx4 v[106:109], v247, s[14:15] offset:96
	global_load_dwordx4 v[110:113], v247, s[14:15] offset:112
	global_load_dwordx4 v[114:117], v247, s[14:15] offset:128
	global_load_dwordx4 v[118:121], v247, s[14:15] offset:144
	global_load_dwordx4 v[122:125], v247, s[14:15] offset:160
	global_load_dwordx4 v[126:129], v247, s[14:15] offset:176
	global_load_dwordx4 v[130:133], v247, s[14:15] offset:192
	global_load_dwordx4 v[134:137], v247, s[14:15] offset:208
	global_load_dwordx4 v[138:141], v247, s[14:15] offset:224
	global_load_dwordx4 v[142:145], v247, s[14:15] offset:240
	s_add_u32 s14, s14, 0x400000
	s_addc_u32 s15, s15, 0
	global_load_dwordx4 v[64:67], v247, s[14:15]
	global_load_dwordx4 v[68:71], v247, s[14:15] offset:16
	global_load_dwordx4 v[72:75], v247, s[14:15] offset:32
	global_load_dwordx4 v[76:79], v247, s[14:15] offset:48
	global_load_dwordx4 v[152:155], v247, s[14:15] offset:64
	global_load_dwordx4 v[156:159], v247, s[14:15] offset:80
	global_load_dwordx4 v[160:163], v247, s[14:15] offset:96
	global_load_dwordx4 v[170:173], v247, s[14:15] offset:112
	global_load_dwordx4 v[174:177], v247, s[14:15] offset:128
	global_load_dwordx4 v[178:181], v247, s[14:15] offset:144
	global_load_dwordx4 v[182:185], v247, s[14:15] offset:160
	global_load_dwordx4 v[220:223], v247, s[14:15] offset:176
	global_load_dwordx4 v[224:227], v247, s[14:15] offset:192
	global_load_dwordx4 v[228:231], v247, s[14:15] offset:208
	global_load_dwordx4 v[232:235], v247, s[14:15] offset:224
	global_load_dwordx4 v[236:239], v247, s[14:15] offset:240
	s_add_u32 s14, s14, 0x400000
	s_addc_u32 s15, s15, 0
	s_waitcnt vmcnt(16)
	v_pk_add_f32 v[0:1], v[0:1], v[82:83]
	v_pk_add_f32 v[2:3], v[2:3], v[84:85]
	v_pk_add_f32 v[4:5], v[4:5], v[86:87]
	v_pk_add_f32 v[6:7], v[6:7], v[88:89]
	v_pk_add_f32 v[8:9], v[8:9], v[90:91]
	v_pk_add_f32 v[10:11], v[10:11], v[92:93]
	v_pk_add_f32 v[12:13], v[12:13], v[94:95]
	v_pk_add_f32 v[14:15], v[14:15], v[96:97]
	v_pk_add_f32 v[16:17], v[16:17], v[98:99]
	v_pk_add_f32 v[18:19], v[18:19], v[100:101]
	v_pk_add_f32 v[20:21], v[20:21], v[102:103]
	v_pk_add_f32 v[22:23], v[22:23], v[104:105]
	v_pk_add_f32 v[24:25], v[24:25], v[106:107]
	v_pk_add_f32 v[26:27], v[26:27], v[108:109]
	v_pk_add_f32 v[28:29], v[28:29], v[110:111]
	v_pk_add_f32 v[30:31], v[30:31], v[112:113]
	v_pk_add_f32 v[32:33], v[32:33], v[114:115]
	v_pk_add_f32 v[34:35], v[34:35], v[116:117]
	v_pk_add_f32 v[36:37], v[36:37], v[118:119]
	v_pk_add_f32 v[38:39], v[38:39], v[120:121]
	v_pk_add_f32 v[40:41], v[40:41], v[122:123]
	v_pk_add_f32 v[42:43], v[42:43], v[124:125]
	v_pk_add_f32 v[44:45], v[44:45], v[126:127]
	v_pk_add_f32 v[46:47], v[46:47], v[128:129]
	v_pk_add_f32 v[48:49], v[48:49], v[130:131]
	v_pk_add_f32 v[50:51], v[50:51], v[132:133]
	v_pk_add_f32 v[52:53], v[52:53], v[134:135]
	v_pk_add_f32 v[54:55], v[54:55], v[136:137]
	v_pk_add_f32 v[56:57], v[56:57], v[138:139]
	v_pk_add_f32 v[58:59], v[58:59], v[140:141]
	v_pk_add_f32 v[60:61], v[60:61], v[142:143]
	v_pk_add_f32 v[62:63], v[62:63], v[144:145]
	global_load_dwordx4 v[82:85], v247, s[14:15]
	global_load_dwordx4 v[86:89], v247, s[14:15] offset:16
	global_load_dwordx4 v[90:93], v247, s[14:15] offset:32
	global_load_dwordx4 v[94:97], v247, s[14:15] offset:48
	global_load_dwordx4 v[98:101], v247, s[14:15] offset:64
	global_load_dwordx4 v[102:105], v247, s[14:15] offset:80
	global_load_dwordx4 v[106:109], v247, s[14:15] offset:96
	global_load_dwordx4 v[110:113], v247, s[14:15] offset:112
	global_load_dwordx4 v[114:117], v247, s[14:15] offset:128
	global_load_dwordx4 v[118:121], v247, s[14:15] offset:144
	global_load_dwordx4 v[122:125], v247, s[14:15] offset:160
	global_load_dwordx4 v[126:129], v247, s[14:15] offset:176
	global_load_dwordx4 v[130:133], v247, s[14:15] offset:192
	global_load_dwordx4 v[134:137], v247, s[14:15] offset:208
	global_load_dwordx4 v[138:141], v247, s[14:15] offset:224
	global_load_dwordx4 v[142:145], v247, s[14:15] offset:240
	s_add_u32 s14, s14, 0x400000
	s_addc_u32 s15, s15, 0
	s_waitcnt vmcnt(16)
; __global__ void __launch_bounds__(512, 2) hybrid_fwd(Params P) {
;     ...
;                 f32x4 hv = *(const f32x4*)((const float*)(ws + WS_SMALL) + kv * 256 + 4 * lane);
;                 { const float* pp = (const float*)(ws + WS_H) + ((size_t)(kv * 4) * 4096 + rr) * 256 + 4 * lane;
; #pragma unroll
;                     for (int ks = 0; ks < 4; ++ks) hv += *(const f32x4*)(pp + (size_t)ks * 4096 * 256);
; #pragma unroll
;                     for (int e = 0; e < 4; ++e) { const float t = hv[e], z = 0.7978845608028654f * (t + 0.044715f * t * t * t);
;                         const float th = 1.0f - 2.0f * __builtin_amdgcn_rcpf(1.0f + __expf(2.0f * z)); hv[e] = 0.5f * t * (1.0f + th); } }
;                 const float* wp = cw2 + (size_t)kv * 256 * 64 + lane; float a = 0.f;
	v_pk_add_f32 v[0:1], v[0:1], v[64:65]
	v_pk_add_f32 v[2:3], v[2:3], v[66:67]
	v_pk_add_f32 v[4:5], v[4:5], v[68:69]
	v_pk_add_f32 v[6:7], v[6:7], v[70:71]
	v_pk_add_f32 v[8:9], v[8:9], v[72:73]
	v_pk_add_f32 v[10:11], v[10:11], v[74:75]
	v_pk_add_f32 v[12:13], v[12:13], v[76:77]
	v_pk_add_f32 v[14:15], v[14:15], v[78:79]
	v_pk_add_f32 v[16:17], v[16:17], v[152:153]
	v_pk_add_f32 v[18:19], v[18:19], v[154:155]
	v_pk_add_f32 v[20:21], v[20:21], v[156:157]
	v_pk_add_f32 v[22:23], v[22:23], v[158:159]
	v_pk_add_f32 v[24:25], v[24:25], v[160:161]
	v_pk_add_f32 v[26:27], v[26:27], v[162:163]
	v_pk_add_f32 v[28:29], v[28:29], v[170:171]
	v_pk_add_f32 v[30:31], v[30:31], v[172:173]
	v_pk_add_f32 v[32:33], v[32:33], v[174:175]
	v_pk_add_f32 v[34:35], v[34:35], v[176:177]
	v_pk_add_f32 v[36:37], v[36:37], v[178:179]
	v_pk_add_f32 v[38:39], v[38:39], v[180:181]
	v_pk_add_f32 v[40:41], v[40:41], v[182:183]
	v_pk_add_f32 v[42:43], v[42:43], v[184:185]
	v_pk_add_f32 v[44:45], v[44:45], v[220:221]
	v_pk_add_f32 v[46:47], v[46:47], v[222:223]
	v_pk_add_f32 v[48:49], v[48:49], v[224:225]
	v_pk_add_f32 v[50:51], v[50:51], v[226:227]
	v_pk_add_f32 v[52:53], v[52:53], v[228:229]
	v_pk_add_f32 v[54:55], v[54:55], v[230:231]
	v_pk_add_f32 v[56:57], v[56:57], v[232:233]
	v_pk_add_f32 v[58:59], v[58:59], v[234:235]
	v_pk_add_f32 v[60:61], v[60:61], v[236:237]
	v_pk_add_f32 v[62:63], v[62:63], v[238:239]
	global_load_dwordx4 v[64:67], v247, s[14:15]
	global_load_dwordx4 v[68:71], v247, s[14:15] offset:16
	global_load_dwordx4 v[72:75], v247, s[14:15] offset:32
	global_load_dwordx4 v[76:79], v247, s[14:15] offset:48
	global_load_dwordx4 v[152:155], v247, s[14:15] offset:64
	global_load_dwordx4 v[156:159], v247, s[14:15] offset:80
	global_load_dwordx4 v[160:163], v247, s[14:15] offset:96
	global_load_dwordx4 v[170:173], v247, s[14:15] offset:112
	global_load_dwordx4 v[174:177], v247, s[14:15] offset:128
	global_load_dwordx4 v[178:181], v247, s[14:15] offset:144
	global_load_dwordx4 v[182:185], v247, s[14:15] offset:160
	global_load_dwordx4 v[220:223], v247, s[14:15] offset:176
	global_load_dwordx4 v[224:227], v247, s[14:15] offset:192
	global_load_dwordx4 v[228:231], v247, s[14:15] offset:208
	global_load_dwordx4 v[232:235], v247, s[14:15] offset:224
	global_load_dwordx4 v[236:239], v247, s[14:15] offset:240
	s_waitcnt vmcnt(16)
	v_pk_add_f32 v[0:1], v[0:1], v[82:83]
	v_pk_add_f32 v[2:3], v[2:3], v[84:85]
	v_pk_add_f32 v[4:5], v[4:5], v[86:87]
	v_pk_add_f32 v[6:7], v[6:7], v[88:89]
	v_pk_add_f32 v[8:9], v[8:9], v[90:91]
	v_pk_add_f32 v[10:11], v[10:11], v[92:93]
	v_pk_add_f32 v[12:13], v[12:13], v[94:95]
	v_pk_add_f32 v[14:15], v[14:15], v[96:97]
	v_pk_add_f32 v[16:17], v[16:17], v[98:99]
	v_pk_add_f32 v[18:19], v[18:19], v[100:101]
	v_pk_add_f32 v[20:21], v[20:21], v[102:103]
	v_pk_add_f32 v[22:23], v[22:23], v[104:105]
	v_pk_add_f32 v[24:25], v[24:25], v[106:107]
	v_pk_add_f32 v[26:27], v[26:27], v[108:109]
	v_pk_add_f32 v[28:29], v[28:29], v[110:111]
	v_pk_add_f32 v[30:31], v[30:31], v[112:113]
	v_pk_add_f32 v[32:33], v[32:33], v[114:115]
	v_pk_add_f32 v[34:35], v[34:35], v[116:117]
	v_pk_add_f32 v[36:37], v[36:37], v[118:119]
	v_pk_add_f32 v[38:39], v[38:39], v[120:121]
	v_pk_add_f32 v[40:41], v[40:41], v[122:123]
	v_pk_add_f32 v[42:43], v[42:43], v[124:125]
	v_pk_add_f32 v[44:45], v[44:45], v[126:127]
	v_pk_add_f32 v[46:47], v[46:47], v[128:129]
	v_pk_add_f32 v[48:49], v[48:49], v[130:131]
	v_pk_add_f32 v[50:51], v[50:51], v[132:133]
	v_pk_add_f32 v[52:53], v[52:53], v[134:135]
	v_pk_add_f32 v[54:55], v[54:55], v[136:137]
	v_pk_add_f32 v[56:57], v[56:57], v[138:139]
	v_pk_add_f32 v[58:59], v[58:59], v[140:141]
	v_pk_add_f32 v[60:61], v[60:61], v[142:143]
	v_pk_add_f32 v[62:63], v[62:63], v[144:145]
	global_load_dwordx4 v[82:85], v249, s[10:11]
	global_load_dwordx4 v[86:89], v249, s[10:11] offset:256
	global_load_dwordx4 v[90:93], v249, s[10:11] offset:512
	global_load_dwordx4 v[94:97], v249, s[10:11] offset:768
	global_load_dwordx4 v[98:101], v249, s[10:11] offset:1024
	global_load_dwordx4 v[102:105], v249, s[10:11] offset:1280
	global_load_dwordx4 v[106:109], v249, s[10:11] offset:1536
	global_load_dwordx4 v[110:113], v249, s[10:11] offset:1792
	s_add_u32 s10, s10, 0x800
	s_addc_u32 s11, s11, 0
	global_load_dwordx4 v[114:117], v249, s[10:11]
	global_load_dwordx4 v[118:121], v249, s[10:11] offset:256
	global_load_dwordx4 v[122:125], v249, s[10:11] offset:512
	global_load_dwordx4 v[126:129], v249, s[10:11] offset:768
	global_load_dwordx4 v[130:133], v249, s[10:11] offset:1024
	global_load_dwordx4 v[134:137], v249, s[10:11] offset:1280
	global_load_dwordx4 v[138:141], v249, s[10:11] offset:1536
	global_load_dwordx4 v[142:145], v249, s[10:11] offset:1792
	s_add_u32 s10, s10, 0x800
	s_addc_u32 s11, s11, 0
	s_waitcnt vmcnt(16)
; __global__ void __launch_bounds__(512, 2) hybrid_fwd(Params P) {
;     ...
;                     for (int ks = 0; ks < 4; ++ks) hv += *(const f32x4*)(pp + (size_t)ks * 4096 * 256);
; #pragma unroll
;                     for (int e = 0; e < 4; ++e) { const float t = hv[e], z = 0.7978845608028654f * (t + 0.044715f * t * t * t);
;                         const float th = 1.0f - 2.0f * __builtin_amdgcn_rcpf(1.0f + __expf(2.0f * z)); hv[e] = 0.5f * t * (1.0f + th); } }
;                 const float* wp = cw2 + (size_t)kv * 256 * 64 + lane; float a = 0.f;
; #pragma unroll
;                 for (int k = 0; k < 256; ++k) { const float hk = __uint_as_float(__builtin_amdgcn_readlane(__float_as_uint(hv[k & 3]), k >> 2)); a = fmaf(hk, wp[k * 64], a); }
	v_pk_add_f32 v[0:1], v[0:1], v[64:65]
	v_pk_add_f32 v[2:3], v[2:3], v[66:67]
	v_pk_add_f32 v[4:5], v[4:5], v[68:69]
	v_pk_add_f32 v[6:7], v[6:7], v[70:71]
	v_pk_add_f32 v[8:9], v[8:9], v[72:73]
	v_pk_add_f32 v[10:11], v[10:11], v[74:75]
	v_pk_add_f32 v[12:13], v[12:13], v[76:77]
	v_pk_add_f32 v[14:15], v[14:15], v[78:79]
	v_pk_add_f32 v[16:17], v[16:17], v[152:153]
	v_pk_add_f32 v[18:19], v[18:19], v[154:155]
	v_pk_add_f32 v[20:21], v[20:21], v[156:157]
	v_pk_add_f32 v[22:23], v[22:23], v[158:159]
	v_pk_add_f32 v[24:25], v[24:25], v[160:161]
	v_pk_add_f32 v[26:27], v[26:27], v[162:163]
	v_pk_add_f32 v[28:29], v[28:29], v[170:171]
	v_pk_add_f32 v[30:31], v[30:31], v[172:173]
	v_pk_add_f32 v[32:33], v[32:33], v[174:175]
	v_pk_add_f32 v[34:35], v[34:35], v[176:177]
	v_pk_add_f32 v[36:37], v[36:37], v[178:179]
	v_pk_add_f32 v[38:39], v[38:39], v[180:181]
	v_pk_add_f32 v[40:41], v[40:41], v[182:183]
	v_pk_add_f32 v[42:43], v[42:43], v[184:185]
	v_pk_add_f32 v[44:45], v[44:45], v[220:221]
	v_pk_add_f32 v[46:47], v[46:47], v[222:223]
	v_pk_add_f32 v[48:49], v[48:49], v[224:225]
	v_pk_add_f32 v[50:51], v[50:51], v[226:227]
	v_pk_add_f32 v[52:53], v[52:53], v[228:229]
	v_pk_add_f32 v[54:55], v[54:55], v[230:231]
	v_pk_add_f32 v[56:57], v[56:57], v[232:233]
	v_pk_add_f32 v[58:59], v[58:59], v[234:235]
	v_pk_add_f32 v[60:61], v[60:61], v[236:237]
	v_pk_add_f32 v[62:63], v[62:63], v[238:239]
	s_mov_b32 s16, 0x3d372713
	s_mov_b32 s18, 0x40135761
	v_mul_f32_e32 v224, v0, v0
	v_mul_f32_e32 v224, v224, v0
	v_fma_f32 v225, s16, v224, v0
	v_mul_f32_e32 v225, s18, v225
	v_exp_f32_e32 v226, v225
	v_mul_f32_e32 v227, 0.5, v0
	s_nop 0
	v_add_f32_e32 v226, 1.0, v226
	v_rcp_f32_e32 v226, v226
	s_nop 0
	v_fma_f32 v226, v226, -2.0, 1.0
	v_fma_f32 v0, v227, v226, v227
	v_mul_f32_e32 v224, v1, v1
	v_mul_f32_e32 v224, v224, v1
	v_fma_f32 v225, s16, v224, v1
	v_mul_f32_e32 v225, s18, v225
	v_exp_f32_e32 v226, v225
	v_mul_f32_e32 v227, 0.5, v1
	s_nop 0
	v_add_f32_e32 v226, 1.0, v226
	v_rcp_f32_e32 v226, v226
	s_nop 0
	v_fma_f32 v226, v226, -2.0, 1.0
	v_fma_f32 v1, v227, v226, v227
	v_mul_f32_e32 v224, v2, v2
	v_mul_f32_e32 v224, v224, v2
	v_fma_f32 v225, s16, v224, v2
	v_mul_f32_e32 v225, s18, v225
	v_exp_f32_e32 v226, v225
	v_mul_f32_e32 v227, 0.5, v2
	s_nop 0
	v_add_f32_e32 v226, 1.0, v226
	v_rcp_f32_e32 v226, v226
	s_nop 0
	v_fma_f32 v226, v226, -2.0, 1.0
	v_fma_f32 v2, v227, v226, v227
	v_mul_f32_e32 v224, v3, v3
	v_mul_f32_e32 v224, v224, v3
	v_fma_f32 v225, s16, v224, v3
	v_mul_f32_e32 v225, s18, v225
	v_exp_f32_e32 v226, v225
	v_mul_f32_e32 v227, 0.5, v3
	s_nop 0
	v_add_f32_e32 v226, 1.0, v226
	v_rcp_f32_e32 v226, v226
	s_nop 0
	v_fma_f32 v226, v226, -2.0, 1.0
	v_fma_f32 v3, v227, v226, v227
	v_mul_f32_e32 v224, v4, v4
	v_mul_f32_e32 v224, v224, v4
	v_fma_f32 v225, s16, v224, v4
	v_mul_f32_e32 v225, s18, v225
	v_exp_f32_e32 v226, v225
	v_mul_f32_e32 v227, 0.5, v4
	s_nop 0
	v_add_f32_e32 v226, 1.0, v226
	v_rcp_f32_e32 v226, v226
	s_nop 0
	v_fma_f32 v226, v226, -2.0, 1.0
	v_fma_f32 v4, v227, v226, v227
	v_mul_f32_e32 v224, v5, v5
	v_mul_f32_e32 v224, v224, v5
	v_fma_f32 v225, s16, v224, v5
	v_mul_f32_e32 v225, s18, v225
	v_exp_f32_e32 v226, v225
	v_mul_f32_e32 v227, 0.5, v5
	s_nop 0
	v_add_f32_e32 v226, 1.0, v226
	v_rcp_f32_e32 v226, v226
	s_nop 0
	v_fma_f32 v226, v226, -2.0, 1.0
	v_fma_f32 v5, v227, v226, v227
	v_mul_f32_e32 v224, v6, v6
	v_mul_f32_e32 v224, v224, v6
	v_fma_f32 v225, s16, v224, v6
	v_mul_f32_e32 v225, s18, v225
	v_exp_f32_e32 v226, v225
	v_mul_f32_e32 v227, 0.5, v6
	s_nop 0
	v_add_f32_e32 v226, 1.0, v226
	v_rcp_f32_e32 v226, v226
	s_nop 0
	v_fma_f32 v226, v226, -2.0, 1.0
	v_fma_f32 v6, v227, v226, v227
	v_mul_f32_e32 v224, v7, v7
	v_mul_f32_e32 v224, v224, v7
	v_fma_f32 v225, s16, v224, v7
	v_mul_f32_e32 v225, s18, v225
	v_exp_f32_e32 v226, v225
	v_mul_f32_e32 v227, 0.5, v7
	s_nop 0
	v_add_f32_e32 v226, 1.0, v226
	v_rcp_f32_e32 v226, v226
	s_nop 0
	v_fma_f32 v226, v226, -2.0, 1.0
	v_fma_f32 v7, v227, v226, v227
	v_mov_b32_e32 v64, 0
	v_mov_b32_e32 v65, 0
	v_mov_b32_e32 v66, 0
	v_mov_b32_e32 v67, 0
	v_mov_b32_e32 v68, 0
	v_mov_b32_e32 v69, 0
	v_mov_b32_e32 v70, 0
	v_mov_b32_e32 v71, 0
	v_mov_b32_e32 v72, 0
	v_mov_b32_e32 v73, 0
	v_mov_b32_e32 v74, 0
	v_mov_b32_e32 v75, 0
	v_mov_b32_e32 v76, 0
	v_mov_b32_e32 v77, 0
	v_mov_b32_e32 v78, 0
	v_mov_b32_e32 v79, 0
	global_load_dwordx4 v[152:155], v249, s[10:11]
	global_load_dwordx4 v[156:159], v249, s[10:11] offset:256
	global_load_dwordx4 v[160:163], v249, s[10:11] offset:512
	global_load_dwordx4 v[170:173], v249, s[10:11] offset:768
	global_load_dwordx4 v[174:177], v249, s[10:11] offset:1024
	global_load_dwordx4 v[178:181], v249, s[10:11] offset:1280
	global_load_dwordx4 v[182:185], v249, s[10:11] offset:1536
	global_load_dwordx4 v[220:223], v249, s[10:11] offset:1792
	s_add_u32 s10, s10, 0x800
	s_addc_u32 s11, s11, 0
	s_waitcnt vmcnt(16)
; __global__ void __launch_bounds__(512, 2) hybrid_fwd(Params P) {
;     ...
;                     for (int e = 0; e < 4; ++e) { const float t = hv[e], z = 0.7978845608028654f * (t + 0.044715f * t * t * t);
;                         const float th = 1.0f - 2.0f * __builtin_amdgcn_rcpf(1.0f + __expf(2.0f * z)); hv[e] = 0.5f * t * (1.0f + th); } }
;                 const float* wp = cw2 + (size_t)kv * 256 * 64 + lane; float a = 0.f;
; #pragma unroll
;                 for (int k = 0; k < 256; ++k) { const float hk = __uint_as_float(__builtin_amdgcn_readlane(__float_as_uint(hv[k & 3]), k >> 2)); a = fmaf(hk, wp[k * 64], a); }
	v_mfma_f32_16x16x4_f32 v[64:67], v0, v82, v[64:67]
	v_mul_f32_e32 v224, v8, v8
	v_mul_f32_e32 v224, v224, v8
	v_fma_f32 v225, s16, v224, v8
	v_mfma_f32_16x16x4_f32 v[68:71], v0, v83, v[68:71]
	v_mul_f32_e32 v225, s18, v225
	v_exp_f32_e32 v226, v225
	v_mul_f32_e32 v227, 0.5, v8
	v_mfma_f32_16x16x4_f32 v[72:75], v0, v84, v[72:75]
	v_add_f32_e32 v226, 1.0, v226
	v_rcp_f32_e32 v226, v226
	v_mfma_f32_16x16x4_f32 v[76:79], v0, v85, v[76:79]
	v_fma_f32 v226, v226, -2.0, 1.0
	v_fma_f32 v8, v227, v226, v227
	v_mfma_f32_16x16x4_f32 v[64:67], v1, v86, v[64:67]
	v_mul_f32_e32 v224, v9, v9
	v_mul_f32_e32 v224, v224, v9
	v_fma_f32 v225, s16, v224, v9
	v_mfma_f32_16x16x4_f32 v[68:71], v1, v87, v[68:71]
	v_mul_f32_e32 v225, s18, v225
	v_exp_f32_e32 v226, v225
	v_mul_f32_e32 v227, 0.5, v9
	v_mfma_f32_16x16x4_f32 v[72:75], v1, v88, v[72:75]
	v_add_f32_e32 v226, 1.0, v226
	v_rcp_f32_e32 v226, v226
	v_mfma_f32_16x16x4_f32 v[76:79], v1, v89, v[76:79]
	v_fma_f32 v226, v226, -2.0, 1.0
	v_fma_f32 v9, v227, v226, v227
	v_mfma_f32_16x16x4_f32 v[64:67], v2, v90, v[64:67]
	v_mul_f32_e32 v224, v10, v10
	v_mul_f32_e32 v224, v224, v10
	v_fma_f32 v225, s16, v224, v10
	v_mfma_f32_16x16x4_f32 v[68:71], v2, v91, v[68:71]
	v_mul_f32_e32 v225, s18, v225
	v_exp_f32_e32 v226, v225
	v_mul_f32_e32 v227, 0.5, v10
	v_mfma_f32_16x16x4_f32 v[72:75], v2, v92, v[72:75]
	v_add_f32_e32 v226, 1.0, v226
	v_rcp_f32_e32 v226, v226
	v_mfma_f32_16x16x4_f32 v[76:79], v2, v93, v[76:79]
	v_fma_f32 v226, v226, -2.0, 1.0
	v_fma_f32 v10, v227, v226, v227
	v_mfma_f32_16x16x4_f32 v[64:67], v3, v94, v[64:67]
	v_mul_f32_e32 v224, v11, v11
	v_mul_f32_e32 v224, v224, v11
	v_fma_f32 v225, s16, v224, v11
	v_mfma_f32_16x16x4_f32 v[68:71], v3, v95, v[68:71]
	v_mul_f32_e32 v225, s18, v225
	v_exp_f32_e32 v226, v225
	v_mul_f32_e32 v227, 0.5, v11
	v_mfma_f32_16x16x4_f32 v[72:75], v3, v96, v[72:75]
	v_add_f32_e32 v226, 1.0, v226
	v_rcp_f32_e32 v226, v226
	v_mfma_f32_16x16x4_f32 v[76:79], v3, v97, v[76:79]
	v_fma_f32 v226, v226, -2.0, 1.0
	v_fma_f32 v11, v227, v226, v227
	v_mfma_f32_16x16x4_f32 v[64:67], v4, v98, v[64:67]
	v_mul_f32_e32 v224, v12, v12
	v_mul_f32_e32 v224, v224, v12
	v_fma_f32 v225, s16, v224, v12
	v_mfma_f32_16x16x4_f32 v[68:71], v4, v99, v[68:71]
	v_mul_f32_e32 v225, s18, v225
	v_exp_f32_e32 v226, v225
	v_mul_f32_e32 v227, 0.5, v12
	v_mfma_f32_16x16x4_f32 v[72:75], v4, v100, v[72:75]
	v_add_f32_e32 v226, 1.0, v226
	v_rcp_f32_e32 v226, v226
	v_mfma_f32_16x16x4_f32 v[76:79], v4, v101, v[76:79]
	v_fma_f32 v226, v226, -2.0, 1.0
	v_fma_f32 v12, v227, v226, v227
	v_mfma_f32_16x16x4_f32 v[64:67], v5, v102, v[64:67]
	v_mul_f32_e32 v224, v13, v13
	v_mul_f32_e32 v224, v224, v13
	v_fma_f32 v225, s16, v224, v13
	v_mfma_f32_16x16x4_f32 v[68:71], v5, v103, v[68:71]
	v_mul_f32_e32 v225, s18, v225
	v_exp_f32_e32 v226, v225
	v_mul_f32_e32 v227, 0.5, v13
	v_mfma_f32_16x16x4_f32 v[72:75], v5, v104, v[72:75]
	v_add_f32_e32 v226, 1.0, v226
	v_rcp_f32_e32 v226, v226
	v_mfma_f32_16x16x4_f32 v[76:79], v5, v105, v[76:79]
	v_fma_f32 v226, v226, -2.0, 1.0
	v_fma_f32 v13, v227, v226, v227
	v_mfma_f32_16x16x4_f32 v[64:67], v6, v106, v[64:67]
	v_mul_f32_e32 v224, v14, v14
	v_mul_f32_e32 v224, v224, v14
	v_fma_f32 v225, s16, v224, v14
	v_mfma_f32_16x16x4_f32 v[68:71], v6, v107, v[68:71]
	v_mul_f32_e32 v225, s18, v225
	v_exp_f32_e32 v226, v225
	v_mul_f32_e32 v227, 0.5, v14
	v_mfma_f32_16x16x4_f32 v[72:75], v6, v108, v[72:75]
	v_add_f32_e32 v226, 1.0, v226
	v_rcp_f32_e32 v226, v226
	v_mfma_f32_16x16x4_f32 v[76:79], v6, v109, v[76:79]
	v_fma_f32 v226, v226, -2.0, 1.0
	v_fma_f32 v14, v227, v226, v227
	v_mfma_f32_16x16x4_f32 v[64:67], v7, v110, v[64:67]
	v_mul_f32_e32 v224, v15, v15
	v_mul_f32_e32 v224, v224, v15
	v_fma_f32 v225, s16, v224, v15
	v_mfma_f32_16x16x4_f32 v[68:71], v7, v111, v[68:71]
	v_mul_f32_e32 v225, s18, v225
	v_exp_f32_e32 v226, v225
	v_mul_f32_e32 v227, 0.5, v15
	v_mfma_f32_16x16x4_f32 v[72:75], v7, v112, v[72:75]
	v_add_f32_e32 v226, 1.0, v226
	v_rcp_f32_e32 v226, v226
	v_mfma_f32_16x16x4_f32 v[76:79], v7, v113, v[76:79]
	v_fma_f32 v226, v226, -2.0, 1.0
	v_fma_f32 v15, v227, v226, v227
	global_load_dwordx4 v[82:85], v249, s[10:11]
	global_load_dwordx4 v[86:89], v249, s[10:11] offset:256
	global_load_dwordx4 v[90:93], v249, s[10:11] offset:512
	global_load_dwordx4 v[94:97], v249, s[10:11] offset:768
	global_load_dwordx4 v[98:101], v249, s[10:11] offset:1024
	global_load_dwordx4 v[102:105], v249, s[10:11] offset:1280
	global_load_dwordx4 v[106:109], v249, s[10:11] offset:1536
	global_load_dwordx4 v[110:113], v249, s[10:11] offset:1792
	s_add_u32 s10, s10, 0x800
	s_addc_u32 s11, s11, 0
	s_waitcnt vmcnt(16)
; __global__ void __launch_bounds__(512, 2) hybrid_fwd(Params P) {
;     ...
;                     for (int e = 0; e < 4; ++e) { const float t = hv[e], z = 0.7978845608028654f * (t + 0.044715f * t * t * t);
;                         const float th = 1.0f - 2.0f * __builtin_amdgcn_rcpf(1.0f + __expf(2.0f * z)); hv[e] = 0.5f * t * (1.0f + th); } }
;                 const float* wp = cw2 + (size_t)kv * 256 * 64 + lane; float a = 0.f;
; #pragma unroll
;                 for (int k = 0; k < 256; ++k) { const float hk = __uint_as_float(__builtin_amdgcn_readlane(__float_as_uint(hv[k & 3]), k >> 2)); a = fmaf(hk, wp[k * 64], a); }
	v_mfma_f32_16x16x4_f32 v[64:67], v8, v114, v[64:67]
	v_mul_f32_e32 v224, v16, v16
	v_mul_f32_e32 v224, v224, v16
	v_fma_f32 v225, s16, v224, v16
	v_mfma_f32_16x16x4_f32 v[68:71], v8, v115, v[68:71]
	v_mul_f32_e32 v225, s18, v225
	v_exp_f32_e32 v226, v225
	v_mul_f32_e32 v227, 0.5, v16
	v_mfma_f32_16x16x4_f32 v[72:75], v8, v116, v[72:75]
	v_add_f32_e32 v226, 1.0, v226
	v_rcp_f32_e32 v226, v226
	v_mfma_f32_16x16x4_f32 v[76:79], v8, v117, v[76:79]
	v_fma_f32 v226, v226, -2.0, 1.0
	v_fma_f32 v16, v227, v226, v227
	v_mfma_f32_16x16x4_f32 v[64:67], v9, v118, v[64:67]
	v_mul_f32_e32 v224, v17, v17
	v_mul_f32_e32 v224, v224, v17
	v_fma_f32 v225, s16, v224, v17
	v_mfma_f32_16x16x4_f32 v[68:71], v9, v119, v[68:71]
	v_mul_f32_e32 v225, s18, v225
	v_exp_f32_e32 v226, v225
	v_mul_f32_e32 v227, 0.5, v17
	v_mfma_f32_16x16x4_f32 v[72:75], v9, v120, v[72:75]
	v_add_f32_e32 v226, 1.0, v226
	v_rcp_f32_e32 v226, v226
	v_mfma_f32_16x16x4_f32 v[76:79], v9, v121, v[76:79]
	v_fma_f32 v226, v226, -2.0, 1.0
	v_fma_f32 v17, v227, v226, v227
	v_mfma_f32_16x16x4_f32 v[64:67], v10, v122, v[64:67]
	v_mul_f32_e32 v224, v18, v18
	v_mul_f32_e32 v224, v224, v18
	v_fma_f32 v225, s16, v224, v18
	v_mfma_f32_16x16x4_f32 v[68:71], v10, v123, v[68:71]
	v_mul_f32_e32 v225, s18, v225
	v_exp_f32_e32 v226, v225
	v_mul_f32_e32 v227, 0.5, v18
	v_mfma_f32_16x16x4_f32 v[72:75], v10, v124, v[72:75]
	v_add_f32_e32 v226, 1.0, v226
	v_rcp_f32_e32 v226, v226
	v_mfma_f32_16x16x4_f32 v[76:79], v10, v125, v[76:79]
	v_fma_f32 v226, v226, -2.0, 1.0
	v_fma_f32 v18, v227, v226, v227
	v_mfma_f32_16x16x4_f32 v[64:67], v11, v126, v[64:67]
	v_mul_f32_e32 v224, v19, v19
	v_mul_f32_e32 v224, v224, v19
	v_fma_f32 v225, s16, v224, v19
	v_mfma_f32_16x16x4_f32 v[68:71], v11, v127, v[68:71]
	v_mul_f32_e32 v225, s18, v225
	v_exp_f32_e32 v226, v225
	v_mul_f32_e32 v227, 0.5, v19
	v_mfma_f32_16x16x4_f32 v[72:75], v11, v128, v[72:75]
	v_add_f32_e32 v226, 1.0, v226
	v_rcp_f32_e32 v226, v226
	v_mfma_f32_16x16x4_f32 v[76:79], v11, v129, v[76:79]
	v_fma_f32 v226, v226, -2.0, 1.0
	v_fma_f32 v19, v227, v226, v227
	v_mfma_f32_16x16x4_f32 v[64:67], v12, v130, v[64:67]
	v_mul_f32_e32 v224, v20, v20
	v_mul_f32_e32 v224, v224, v20
	v_fma_f32 v225, s16, v224, v20
	v_mfma_f32_16x16x4_f32 v[68:71], v12, v131, v[68:71]
	v_mul_f32_e32 v225, s18, v225
	v_exp_f32_e32 v226, v225
	v_mul_f32_e32 v227, 0.5, v20
	v_mfma_f32_16x16x4_f32 v[72:75], v12, v132, v[72:75]
	v_add_f32_e32 v226, 1.0, v226
	v_rcp_f32_e32 v226, v226
	v_mfma_f32_16x16x4_f32 v[76:79], v12, v133, v[76:79]
	v_fma_f32 v226, v226, -2.0, 1.0
	v_fma_f32 v20, v227, v226, v227
	v_mfma_f32_16x16x4_f32 v[64:67], v13, v134, v[64:67]
	v_mul_f32_e32 v224, v21, v21
	v_mul_f32_e32 v224, v224, v21
	v_fma_f32 v225, s16, v224, v21
	v_mfma_f32_16x16x4_f32 v[68:71], v13, v135, v[68:71]
	v_mul_f32_e32 v225, s18, v225
	v_exp_f32_e32 v226, v225
	v_mul_f32_e32 v227, 0.5, v21
	v_mfma_f32_16x16x4_f32 v[72:75], v13, v136, v[72:75]
	v_add_f32_e32 v226, 1.0, v226
	v_rcp_f32_e32 v226, v226
	v_mfma_f32_16x16x4_f32 v[76:79], v13, v137, v[76:79]
	v_fma_f32 v226, v226, -2.0, 1.0
	v_fma_f32 v21, v227, v226, v227
	v_mfma_f32_16x16x4_f32 v[64:67], v14, v138, v[64:67]
	v_mul_f32_e32 v224, v22, v22
	v_mul_f32_e32 v224, v224, v22
	v_fma_f32 v225, s16, v224, v22
	v_mfma_f32_16x16x4_f32 v[68:71], v14, v139, v[68:71]
	v_mul_f32_e32 v225, s18, v225
	v_exp_f32_e32 v226, v225
	v_mul_f32_e32 v227, 0.5, v22
	v_mfma_f32_16x16x4_f32 v[72:75], v14, v140, v[72:75]
	v_add_f32_e32 v226, 1.0, v226
	v_rcp_f32_e32 v226, v226
	v_mfma_f32_16x16x4_f32 v[76:79], v14, v141, v[76:79]
	v_fma_f32 v226, v226, -2.0, 1.0
	v_fma_f32 v22, v227, v226, v227
	v_mfma_f32_16x16x4_f32 v[64:67], v15, v142, v[64:67]
	v_mul_f32_e32 v224, v23, v23
	v_mul_f32_e32 v224, v224, v23
	v_fma_f32 v225, s16, v224, v23
	v_mfma_f32_16x16x4_f32 v[68:71], v15, v143, v[68:71]
	v_mul_f32_e32 v225, s18, v225
	v_exp_f32_e32 v226, v225
	v_mul_f32_e32 v227, 0.5, v23
	v_mfma_f32_16x16x4_f32 v[72:75], v15, v144, v[72:75]
	v_add_f32_e32 v226, 1.0, v226
	v_rcp_f32_e32 v226, v226
	v_mfma_f32_16x16x4_f32 v[76:79], v15, v145, v[76:79]
	v_fma_f32 v226, v226, -2.0, 1.0
	v_fma_f32 v23, v227, v226, v227
	global_load_dwordx4 v[114:117], v249, s[10:11]
	global_load_dwordx4 v[118:121], v249, s[10:11] offset:256
	global_load_dwordx4 v[122:125], v249, s[10:11] offset:512
	global_load_dwordx4 v[126:129], v249, s[10:11] offset:768
	global_load_dwordx4 v[130:133], v249, s[10:11] offset:1024
	global_load_dwordx4 v[134:137], v249, s[10:11] offset:1280
	global_load_dwordx4 v[138:141], v249, s[10:11] offset:1536
	global_load_dwordx4 v[142:145], v249, s[10:11] offset:1792
	s_add_u32 s10, s10, 0x800
	s_addc_u32 s11, s11, 0
	s_waitcnt vmcnt(16)
; __global__ void __launch_bounds__(512, 2) hybrid_fwd(Params P) {
;     ...
;                     for (int e = 0; e < 4; ++e) { const float t = hv[e], z = 0.7978845608028654f * (t + 0.044715f * t * t * t);
;                         const float th = 1.0f - 2.0f * __builtin_amdgcn_rcpf(1.0f + __expf(2.0f * z)); hv[e] = 0.5f * t * (1.0f + th); } }
;                 const float* wp = cw2 + (size_t)kv * 256 * 64 + lane; float a = 0.f;
; #pragma unroll
;                 for (int k = 0; k < 256; ++k) { const float hk = __uint_as_float(__builtin_amdgcn_readlane(__float_as_uint(hv[k & 3]), k >> 2)); a = fmaf(hk, wp[k * 64], a); }
	v_mfma_f32_16x16x4_f32 v[64:67], v16, v152, v[64:67]
	v_mul_f32_e32 v224, v24, v24
	v_mul_f32_e32 v224, v224, v24
	v_fma_f32 v225, s16, v224, v24
	v_mfma_f32_16x16x4_f32 v[68:71], v16, v153, v[68:71]
	v_mul_f32_e32 v225, s18, v225
	v_exp_f32_e32 v226, v225
	v_mul_f32_e32 v227, 0.5, v24
	v_mfma_f32_16x16x4_f32 v[72:75], v16, v154, v[72:75]
	v_add_f32_e32 v226, 1.0, v226
	v_rcp_f32_e32 v226, v226
	v_mfma_f32_16x16x4_f32 v[76:79], v16, v155, v[76:79]
	v_fma_f32 v226, v226, -2.0, 1.0
	v_fma_f32 v24, v227, v226, v227
	v_mfma_f32_16x16x4_f32 v[64:67], v17, v156, v[64:67]
	v_mul_f32_e32 v224, v25, v25
	v_mul_f32_e32 v224, v224, v25
	v_fma_f32 v225, s16, v224, v25
	v_mfma_f32_16x16x4_f32 v[68:71], v17, v157, v[68:71]
	v_mul_f32_e32 v225, s18, v225
	v_exp_f32_e32 v226, v225
	v_mul_f32_e32 v227, 0.5, v25
	v_mfma_f32_16x16x4_f32 v[72:75], v17, v158, v[72:75]
	v_add_f32_e32 v226, 1.0, v226
	v_rcp_f32_e32 v226, v226
	v_mfma_f32_16x16x4_f32 v[76:79], v17, v159, v[76:79]
	v_fma_f32 v226, v226, -2.0, 1.0
	v_fma_f32 v25, v227, v226, v227
	v_mfma_f32_16x16x4_f32 v[64:67], v18, v160, v[64:67]
	v_mul_f32_e32 v224, v26, v26
	v_mul_f32_e32 v224, v224, v26
	v_fma_f32 v225, s16, v224, v26
	v_mfma_f32_16x16x4_f32 v[68:71], v18, v161, v[68:71]
	v_mul_f32_e32 v225, s18, v225
	v_exp_f32_e32 v226, v225
	v_mul_f32_e32 v227, 0.5, v26
	v_mfma_f32_16x16x4_f32 v[72:75], v18, v162, v[72:75]
	v_add_f32_e32 v226, 1.0, v226
	v_rcp_f32_e32 v226, v226
	v_mfma_f32_16x16x4_f32 v[76:79], v18, v163, v[76:79]
	v_fma_f32 v226, v226, -2.0, 1.0
	v_fma_f32 v26, v227, v226, v227
	v_mfma_f32_16x16x4_f32 v[64:67], v19, v170, v[64:67]
	v_mul_f32_e32 v224, v27, v27
	v_mul_f32_e32 v224, v224, v27
	v_fma_f32 v225, s16, v224, v27
	v_mfma_f32_16x16x4_f32 v[68:71], v19, v171, v[68:71]
	v_mul_f32_e32 v225, s18, v225
	v_exp_f32_e32 v226, v225
	v_mul_f32_e32 v227, 0.5, v27
	v_mfma_f32_16x16x4_f32 v[72:75], v19, v172, v[72:75]
	v_add_f32_e32 v226, 1.0, v226
	v_rcp_f32_e32 v226, v226
	v_mfma_f32_16x16x4_f32 v[76:79], v19, v173, v[76:79]
	v_fma_f32 v226, v226, -2.0, 1.0
	v_fma_f32 v27, v227, v226, v227
	v_mfma_f32_16x16x4_f32 v[64:67], v20, v174, v[64:67]
	v_mul_f32_e32 v224, v28, v28
	v_mul_f32_e32 v224, v224, v28
	v_fma_f32 v225, s16, v224, v28
	v_mfma_f32_16x16x4_f32 v[68:71], v20, v175, v[68:71]
	v_mul_f32_e32 v225, s18, v225
	v_exp_f32_e32 v226, v225
	v_mul_f32_e32 v227, 0.5, v28
	v_mfma_f32_16x16x4_f32 v[72:75], v20, v176, v[72:75]
	v_add_f32_e32 v226, 1.0, v226
	v_rcp_f32_e32 v226, v226
	v_mfma_f32_16x16x4_f32 v[76:79], v20, v177, v[76:79]
	v_fma_f32 v226, v226, -2.0, 1.0
	v_fma_f32 v28, v227, v226, v227
	v_mfma_f32_16x16x4_f32 v[64:67], v21, v178, v[64:67]
	v_mul_f32_e32 v224, v29, v29
	v_mul_f32_e32 v224, v224, v29
	v_fma_f32 v225, s16, v224, v29
	v_mfma_f32_16x16x4_f32 v[68:71], v21, v179, v[68:71]
	v_mul_f32_e32 v225, s18, v225
	v_exp_f32_e32 v226, v225
	v_mul_f32_e32 v227, 0.5, v29
	v_mfma_f32_16x16x4_f32 v[72:75], v21, v180, v[72:75]
	v_add_f32_e32 v226, 1.0, v226
	v_rcp_f32_e32 v226, v226
	v_mfma_f32_16x16x4_f32 v[76:79], v21, v181, v[76:79]
	v_fma_f32 v226, v226, -2.0, 1.0
	v_fma_f32 v29, v227, v226, v227
	v_mfma_f32_16x16x4_f32 v[64:67], v22, v182, v[64:67]
	v_mul_f32_e32 v224, v30, v30
	v_mul_f32_e32 v224, v224, v30
	v_fma_f32 v225, s16, v224, v30
	v_mfma_f32_16x16x4_f32 v[68:71], v22, v183, v[68:71]
	v_mul_f32_e32 v225, s18, v225
	v_exp_f32_e32 v226, v225
	v_mul_f32_e32 v227, 0.5, v30
	v_mfma_f32_16x16x4_f32 v[72:75], v22, v184, v[72:75]
	v_add_f32_e32 v226, 1.0, v226
	v_rcp_f32_e32 v226, v226
	v_mfma_f32_16x16x4_f32 v[76:79], v22, v185, v[76:79]
	v_fma_f32 v226, v226, -2.0, 1.0
	v_fma_f32 v30, v227, v226, v227
	v_mfma_f32_16x16x4_f32 v[64:67], v23, v220, v[64:67]
	v_mul_f32_e32 v224, v31, v31
	v_mul_f32_e32 v224, v224, v31
	v_fma_f32 v225, s16, v224, v31
	v_mfma_f32_16x16x4_f32 v[68:71], v23, v221, v[68:71]
	v_mul_f32_e32 v225, s18, v225
	v_exp_f32_e32 v226, v225
	v_mul_f32_e32 v227, 0.5, v31
	v_mfma_f32_16x16x4_f32 v[72:75], v23, v222, v[72:75]
	v_add_f32_e32 v226, 1.0, v226
	v_rcp_f32_e32 v226, v226
	v_mfma_f32_16x16x4_f32 v[76:79], v23, v223, v[76:79]
	v_fma_f32 v226, v226, -2.0, 1.0
	v_fma_f32 v31, v227, v226, v227
	global_load_dwordx4 v[152:155], v249, s[10:11]
	global_load_dwordx4 v[156:159], v249, s[10:11] offset:256
	global_load_dwordx4 v[160:163], v249, s[10:11] offset:512
	global_load_dwordx4 v[170:173], v249, s[10:11] offset:768
	global_load_dwordx4 v[174:177], v249, s[10:11] offset:1024
	global_load_dwordx4 v[178:181], v249, s[10:11] offset:1280
	global_load_dwordx4 v[182:185], v249, s[10:11] offset:1536
	global_load_dwordx4 v[220:223], v249, s[10:11] offset:1792
	s_add_u32 s10, s10, 0x800
	s_addc_u32 s11, s11, 0
	s_waitcnt vmcnt(16)
; __global__ void __launch_bounds__(512, 2) hybrid_fwd(Params P) {
;     ...
;                     for (int e = 0; e < 4; ++e) { const float t = hv[e], z = 0.7978845608028654f * (t + 0.044715f * t * t * t);
;                         const float th = 1.0f - 2.0f * __builtin_amdgcn_rcpf(1.0f + __expf(2.0f * z)); hv[e] = 0.5f * t * (1.0f + th); } }
;                 const float* wp = cw2 + (size_t)kv * 256 * 64 + lane; float a = 0.f;
; #pragma unroll
;                 for (int k = 0; k < 256; ++k) { const float hk = __uint_as_float(__builtin_amdgcn_readlane(__float_as_uint(hv[k & 3]), k >> 2)); a = fmaf(hk, wp[k * 64], a); }
	v_mfma_f32_16x16x4_f32 v[64:67], v24, v82, v[64:67]
	v_mul_f32_e32 v224, v32, v32
	v_mul_f32_e32 v224, v224, v32
	v_fma_f32 v225, s16, v224, v32
	v_mfma_f32_16x16x4_f32 v[68:71], v24, v83, v[68:71]
	v_mul_f32_e32 v225, s18, v225
	v_exp_f32_e32 v226, v225
	v_mul_f32_e32 v227, 0.5, v32
	v_mfma_f32_16x16x4_f32 v[72:75], v24, v84, v[72:75]
	v_add_f32_e32 v226, 1.0, v226
	v_rcp_f32_e32 v226, v226
	v_mfma_f32_16x16x4_f32 v[76:79], v24, v85, v[76:79]
	v_fma_f32 v226, v226, -2.0, 1.0
	v_fma_f32 v32, v227, v226, v227
	v_mfma_f32_16x16x4_f32 v[64:67], v25, v86, v[64:67]
	v_mul_f32_e32 v224, v33, v33
	v_mul_f32_e32 v224, v224, v33
	v_fma_f32 v225, s16, v224, v33
	v_mfma_f32_16x16x4_f32 v[68:71], v25, v87, v[68:71]
	v_mul_f32_e32 v225, s18, v225
	v_exp_f32_e32 v226, v225
	v_mul_f32_e32 v227, 0.5, v33
	v_mfma_f32_16x16x4_f32 v[72:75], v25, v88, v[72:75]
	v_add_f32_e32 v226, 1.0, v226
	v_rcp_f32_e32 v226, v226
	v_mfma_f32_16x16x4_f32 v[76:79], v25, v89, v[76:79]
	v_fma_f32 v226, v226, -2.0, 1.0
	v_fma_f32 v33, v227, v226, v227
	v_mfma_f32_16x16x4_f32 v[64:67], v26, v90, v[64:67]
	v_mul_f32_e32 v224, v34, v34
	v_mul_f32_e32 v224, v224, v34
	v_fma_f32 v225, s16, v224, v34
	v_mfma_f32_16x16x4_f32 v[68:71], v26, v91, v[68:71]
	v_mul_f32_e32 v225, s18, v225
	v_exp_f32_e32 v226, v225
	v_mul_f32_e32 v227, 0.5, v34
	v_mfma_f32_16x16x4_f32 v[72:75], v26, v92, v[72:75]
	v_add_f32_e32 v226, 1.0, v226
	v_rcp_f32_e32 v226, v226
	v_mfma_f32_16x16x4_f32 v[76:79], v26, v93, v[76:79]
	v_fma_f32 v226, v226, -2.0, 1.0
	v_fma_f32 v34, v227, v226, v227
	v_mfma_f32_16x16x4_f32 v[64:67], v27, v94, v[64:67]
	v_mul_f32_e32 v224, v35, v35
	v_mul_f32_e32 v224, v224, v35
	v_fma_f32 v225, s16, v224, v35
	v_mfma_f32_16x16x4_f32 v[68:71], v27, v95, v[68:71]
	v_mul_f32_e32 v225, s18, v225
	v_exp_f32_e32 v226, v225
	v_mul_f32_e32 v227, 0.5, v35
	v_mfma_f32_16x16x4_f32 v[72:75], v27, v96, v[72:75]
	v_add_f32_e32 v226, 1.0, v226
	v_rcp_f32_e32 v226, v226
	v_mfma_f32_16x16x4_f32 v[76:79], v27, v97, v[76:79]
	v_fma_f32 v226, v226, -2.0, 1.0
	v_fma_f32 v35, v227, v226, v227
	v_mfma_f32_16x16x4_f32 v[64:67], v28, v98, v[64:67]
	v_mul_f32_e32 v224, v36, v36
	v_mul_f32_e32 v224, v224, v36
	v_fma_f32 v225, s16, v224, v36
	v_mfma_f32_16x16x4_f32 v[68:71], v28, v99, v[68:71]
	v_mul_f32_e32 v225, s18, v225
	v_exp_f32_e32 v226, v225
	v_mul_f32_e32 v227, 0.5, v36
	v_mfma_f32_16x16x4_f32 v[72:75], v28, v100, v[72:75]
	v_add_f32_e32 v226, 1.0, v226
	v_rcp_f32_e32 v226, v226
	v_mfma_f32_16x16x4_f32 v[76:79], v28, v101, v[76:79]
	v_fma_f32 v226, v226, -2.0, 1.0
	v_fma_f32 v36, v227, v226, v227
	v_mfma_f32_16x16x4_f32 v[64:67], v29, v102, v[64:67]
	v_mul_f32_e32 v224, v37, v37
	v_mul_f32_e32 v224, v224, v37
	v_fma_f32 v225, s16, v224, v37
	v_mfma_f32_16x16x4_f32 v[68:71], v29, v103, v[68:71]
	v_mul_f32_e32 v225, s18, v225
	v_exp_f32_e32 v226, v225
	v_mul_f32_e32 v227, 0.5, v37
	v_mfma_f32_16x16x4_f32 v[72:75], v29, v104, v[72:75]
	v_add_f32_e32 v226, 1.0, v226
	v_rcp_f32_e32 v226, v226
	v_mfma_f32_16x16x4_f32 v[76:79], v29, v105, v[76:79]
	v_fma_f32 v226, v226, -2.0, 1.0
	v_fma_f32 v37, v227, v226, v227
	v_mfma_f32_16x16x4_f32 v[64:67], v30, v106, v[64:67]
	v_mul_f32_e32 v224, v38, v38
	v_mul_f32_e32 v224, v224, v38
	v_fma_f32 v225, s16, v224, v38
	v_mfma_f32_16x16x4_f32 v[68:71], v30, v107, v[68:71]
	v_mul_f32_e32 v225, s18, v225
	v_exp_f32_e32 v226, v225
	v_mul_f32_e32 v227, 0.5, v38
	v_mfma_f32_16x16x4_f32 v[72:75], v30, v108, v[72:75]
	v_add_f32_e32 v226, 1.0, v226
	v_rcp_f32_e32 v226, v226
	v_mfma_f32_16x16x4_f32 v[76:79], v30, v109, v[76:79]
	v_fma_f32 v226, v226, -2.0, 1.0
	v_fma_f32 v38, v227, v226, v227
	v_mfma_f32_16x16x4_f32 v[64:67], v31, v110, v[64:67]
	v_mul_f32_e32 v224, v39, v39
	v_mul_f32_e32 v224, v224, v39
	v_fma_f32 v225, s16, v224, v39
	v_mfma_f32_16x16x4_f32 v[68:71], v31, v111, v[68:71]
	v_mul_f32_e32 v225, s18, v225
	v_exp_f32_e32 v226, v225
	v_mul_f32_e32 v227, 0.5, v39
	v_mfma_f32_16x16x4_f32 v[72:75], v31, v112, v[72:75]
	v_add_f32_e32 v226, 1.0, v226
	v_rcp_f32_e32 v226, v226
	v_mfma_f32_16x16x4_f32 v[76:79], v31, v113, v[76:79]
	v_fma_f32 v226, v226, -2.0, 1.0
	v_fma_f32 v39, v227, v226, v227
	global_load_dwordx4 v[82:85], v249, s[10:11]
	global_load_dwordx4 v[86:89], v249, s[10:11] offset:256
	global_load_dwordx4 v[90:93], v249, s[10:11] offset:512
	global_load_dwordx4 v[94:97], v249, s[10:11] offset:768
	global_load_dwordx4 v[98:101], v249, s[10:11] offset:1024
	global_load_dwordx4 v[102:105], v249, s[10:11] offset:1280
	global_load_dwordx4 v[106:109], v249, s[10:11] offset:1536
	global_load_dwordx4 v[110:113], v249, s[10:11] offset:1792
	s_add_u32 s10, s10, 0x800
	s_addc_u32 s11, s11, 0
	s_waitcnt vmcnt(16)
; __global__ void __launch_bounds__(512, 2) hybrid_fwd(Params P) {
;     ...
;                     for (int e = 0; e < 4; ++e) { const float t = hv[e], z = 0.7978845608028654f * (t + 0.044715f * t * t * t);
;                         const float th = 1.0f - 2.0f * __builtin_amdgcn_rcpf(1.0f + __expf(2.0f * z)); hv[e] = 0.5f * t * (1.0f + th); } }
;                 const float* wp = cw2 + (size_t)kv * 256 * 64 + lane; float a = 0.f;
; #pragma unroll
;                 for (int k = 0; k < 256; ++k) { const float hk = __uint_as_float(__builtin_amdgcn_readlane(__float_as_uint(hv[k & 3]), k >> 2)); a = fmaf(hk, wp[k * 64], a); }
	v_mfma_f32_16x16x4_f32 v[64:67], v32, v114, v[64:67]
	v_mul_f32_e32 v224, v40, v40
	v_mul_f32_e32 v224, v224, v40
	v_fma_f32 v225, s16, v224, v40
	v_mfma_f32_16x16x4_f32 v[68:71], v32, v115, v[68:71]
	v_mul_f32_e32 v225, s18, v225
	v_exp_f32_e32 v226, v225
	v_mul_f32_e32 v227, 0.5, v40
	v_mfma_f32_16x16x4_f32 v[72:75], v32, v116, v[72:75]
	v_add_f32_e32 v226, 1.0, v226
	v_rcp_f32_e32 v226, v226
	v_mfma_f32_16x16x4_f32 v[76:79], v32, v117, v[76:79]
	v_fma_f32 v226, v226, -2.0, 1.0
	v_fma_f32 v40, v227, v226, v227
	v_mfma_f32_16x16x4_f32 v[64:67], v33, v118, v[64:67]
	v_mul_f32_e32 v224, v41, v41
	v_mul_f32_e32 v224, v224, v41
	v_fma_f32 v225, s16, v224, v41
	v_mfma_f32_16x16x4_f32 v[68:71], v33, v119, v[68:71]
	v_mul_f32_e32 v225, s18, v225
	v_exp_f32_e32 v226, v225
	v_mul_f32_e32 v227, 0.5, v41
	v_mfma_f32_16x16x4_f32 v[72:75], v33, v120, v[72:75]
	v_add_f32_e32 v226, 1.0, v226
	v_rcp_f32_e32 v226, v226
	v_mfma_f32_16x16x4_f32 v[76:79], v33, v121, v[76:79]
	v_fma_f32 v226, v226, -2.0, 1.0
	v_fma_f32 v41, v227, v226, v227
	v_mfma_f32_16x16x4_f32 v[64:67], v34, v122, v[64:67]
	v_mul_f32_e32 v224, v42, v42
	v_mul_f32_e32 v224, v224, v42
	v_fma_f32 v225, s16, v224, v42
	v_mfma_f32_16x16x4_f32 v[68:71], v34, v123, v[68:71]
	v_mul_f32_e32 v225, s18, v225
	v_exp_f32_e32 v226, v225
	v_mul_f32_e32 v227, 0.5, v42
	v_mfma_f32_16x16x4_f32 v[72:75], v34, v124, v[72:75]
	v_add_f32_e32 v226, 1.0, v226
	v_rcp_f32_e32 v226, v226
	v_mfma_f32_16x16x4_f32 v[76:79], v34, v125, v[76:79]
	v_fma_f32 v226, v226, -2.0, 1.0
	v_fma_f32 v42, v227, v226, v227
	v_mfma_f32_16x16x4_f32 v[64:67], v35, v126, v[64:67]
	v_mul_f32_e32 v224, v43, v43
	v_mul_f32_e32 v224, v224, v43
	v_fma_f32 v225, s16, v224, v43
	v_mfma_f32_16x16x4_f32 v[68:71], v35, v127, v[68:71]
	v_mul_f32_e32 v225, s18, v225
	v_exp_f32_e32 v226, v225
	v_mul_f32_e32 v227, 0.5, v43
	v_mfma_f32_16x16x4_f32 v[72:75], v35, v128, v[72:75]
	v_add_f32_e32 v226, 1.0, v226
	v_rcp_f32_e32 v226, v226
	v_mfma_f32_16x16x4_f32 v[76:79], v35, v129, v[76:79]
	v_fma_f32 v226, v226, -2.0, 1.0
	v_fma_f32 v43, v227, v226, v227
	v_mfma_f32_16x16x4_f32 v[64:67], v36, v130, v[64:67]
	v_mul_f32_e32 v224, v44, v44
	v_mul_f32_e32 v224, v224, v44
	v_fma_f32 v225, s16, v224, v44
	v_mfma_f32_16x16x4_f32 v[68:71], v36, v131, v[68:71]
	v_mul_f32_e32 v225, s18, v225
	v_exp_f32_e32 v226, v225
	v_mul_f32_e32 v227, 0.5, v44
	v_mfma_f32_16x16x4_f32 v[72:75], v36, v132, v[72:75]
	v_add_f32_e32 v226, 1.0, v226
	v_rcp_f32_e32 v226, v226
	v_mfma_f32_16x16x4_f32 v[76:79], v36, v133, v[76:79]
	v_fma_f32 v226, v226, -2.0, 1.0
	v_fma_f32 v44, v227, v226, v227
	v_mfma_f32_16x16x4_f32 v[64:67], v37, v134, v[64:67]
	v_mul_f32_e32 v224, v45, v45
	v_mul_f32_e32 v224, v224, v45
	v_fma_f32 v225, s16, v224, v45
	v_mfma_f32_16x16x4_f32 v[68:71], v37, v135, v[68:71]
	v_mul_f32_e32 v225, s18, v225
	v_exp_f32_e32 v226, v225
	v_mul_f32_e32 v227, 0.5, v45
	v_mfma_f32_16x16x4_f32 v[72:75], v37, v136, v[72:75]
	v_add_f32_e32 v226, 1.0, v226
	v_rcp_f32_e32 v226, v226
	v_mfma_f32_16x16x4_f32 v[76:79], v37, v137, v[76:79]
	v_fma_f32 v226, v226, -2.0, 1.0
	v_fma_f32 v45, v227, v226, v227
	v_mfma_f32_16x16x4_f32 v[64:67], v38, v138, v[64:67]
	v_mul_f32_e32 v224, v46, v46
	v_mul_f32_e32 v224, v224, v46
	v_fma_f32 v225, s16, v224, v46
	v_mfma_f32_16x16x4_f32 v[68:71], v38, v139, v[68:71]
	v_mul_f32_e32 v225, s18, v225
	v_exp_f32_e32 v226, v225
	v_mul_f32_e32 v227, 0.5, v46
	v_mfma_f32_16x16x4_f32 v[72:75], v38, v140, v[72:75]
	v_add_f32_e32 v226, 1.0, v226
	v_rcp_f32_e32 v226, v226
	v_mfma_f32_16x16x4_f32 v[76:79], v38, v141, v[76:79]
	v_fma_f32 v226, v226, -2.0, 1.0
	v_fma_f32 v46, v227, v226, v227
	v_mfma_f32_16x16x4_f32 v[64:67], v39, v142, v[64:67]
	v_mul_f32_e32 v224, v47, v47
	v_mul_f32_e32 v224, v224, v47
	v_fma_f32 v225, s16, v224, v47
	v_mfma_f32_16x16x4_f32 v[68:71], v39, v143, v[68:71]
	v_mul_f32_e32 v225, s18, v225
	v_exp_f32_e32 v226, v225
	v_mul_f32_e32 v227, 0.5, v47
	v_mfma_f32_16x16x4_f32 v[72:75], v39, v144, v[72:75]
	v_add_f32_e32 v226, 1.0, v226
	v_rcp_f32_e32 v226, v226
	v_mfma_f32_16x16x4_f32 v[76:79], v39, v145, v[76:79]
	v_fma_f32 v226, v226, -2.0, 1.0
	v_fma_f32 v47, v227, v226, v227
	global_load_dwordx4 v[114:117], v249, s[10:11]
	global_load_dwordx4 v[118:121], v249, s[10:11] offset:256
	global_load_dwordx4 v[122:125], v249, s[10:11] offset:512
	global_load_dwordx4 v[126:129], v249, s[10:11] offset:768
	global_load_dwordx4 v[130:133], v249, s[10:11] offset:1024
	global_load_dwordx4 v[134:137], v249, s[10:11] offset:1280
	global_load_dwordx4 v[138:141], v249, s[10:11] offset:1536
	global_load_dwordx4 v[142:145], v249, s[10:11] offset:1792
	s_add_u32 s10, s10, 0x800
	s_addc_u32 s11, s11, 0
	s_waitcnt vmcnt(16)
; __global__ void __launch_bounds__(512, 2) hybrid_fwd(Params P) {
;     ...
;                     for (int e = 0; e < 4; ++e) { const float t = hv[e], z = 0.7978845608028654f * (t + 0.044715f * t * t * t);
;                         const float th = 1.0f - 2.0f * __builtin_amdgcn_rcpf(1.0f + __expf(2.0f * z)); hv[e] = 0.5f * t * (1.0f + th); } }
;                 const float* wp = cw2 + (size_t)kv * 256 * 64 + lane; float a = 0.f;
; #pragma unroll
;                 for (int k = 0; k < 256; ++k) { const float hk = __uint_as_float(__builtin_amdgcn_readlane(__float_as_uint(hv[k & 3]), k >> 2)); a = fmaf(hk, wp[k * 64], a); }
	v_mfma_f32_16x16x4_f32 v[64:67], v40, v152, v[64:67]
	v_mul_f32_e32 v224, v48, v48
	v_mul_f32_e32 v224, v224, v48
	v_fma_f32 v225, s16, v224, v48
	v_mfma_f32_16x16x4_f32 v[68:71], v40, v153, v[68:71]
	v_mul_f32_e32 v225, s18, v225
	v_exp_f32_e32 v226, v225
	v_mul_f32_e32 v227, 0.5, v48
	v_mfma_f32_16x16x4_f32 v[72:75], v40, v154, v[72:75]
	v_add_f32_e32 v226, 1.0, v226
	v_rcp_f32_e32 v226, v226
	v_mfma_f32_16x16x4_f32 v[76:79], v40, v155, v[76:79]
	v_fma_f32 v226, v226, -2.0, 1.0
	v_fma_f32 v48, v227, v226, v227
	v_mfma_f32_16x16x4_f32 v[64:67], v41, v156, v[64:67]
	v_mul_f32_e32 v224, v49, v49
	v_mul_f32_e32 v224, v224, v49
	v_fma_f32 v225, s16, v224, v49
	v_mfma_f32_16x16x4_f32 v[68:71], v41, v157, v[68:71]
	v_mul_f32_e32 v225, s18, v225
	v_exp_f32_e32 v226, v225
	v_mul_f32_e32 v227, 0.5, v49
	v_mfma_f32_16x16x4_f32 v[72:75], v41, v158, v[72:75]
	v_add_f32_e32 v226, 1.0, v226
	v_rcp_f32_e32 v226, v226
	v_mfma_f32_16x16x4_f32 v[76:79], v41, v159, v[76:79]
	v_fma_f32 v226, v226, -2.0, 1.0
	v_fma_f32 v49, v227, v226, v227
	v_mfma_f32_16x16x4_f32 v[64:67], v42, v160, v[64:67]
	v_mul_f32_e32 v224, v50, v50
	v_mul_f32_e32 v224, v224, v50
	v_fma_f32 v225, s16, v224, v50
	v_mfma_f32_16x16x4_f32 v[68:71], v42, v161, v[68:71]
	v_mul_f32_e32 v225, s18, v225
	v_exp_f32_e32 v226, v225
	v_mul_f32_e32 v227, 0.5, v50
	v_mfma_f32_16x16x4_f32 v[72:75], v42, v162, v[72:75]
	v_add_f32_e32 v226, 1.0, v226
	v_rcp_f32_e32 v226, v226
	v_mfma_f32_16x16x4_f32 v[76:79], v42, v163, v[76:79]
	v_fma_f32 v226, v226, -2.0, 1.0
	v_fma_f32 v50, v227, v226, v227
	v_mfma_f32_16x16x4_f32 v[64:67], v43, v170, v[64:67]
	v_mul_f32_e32 v224, v51, v51
	v_mul_f32_e32 v224, v224, v51
	v_fma_f32 v225, s16, v224, v51
	v_mfma_f32_16x16x4_f32 v[68:71], v43, v171, v[68:71]
	v_mul_f32_e32 v225, s18, v225
	v_exp_f32_e32 v226, v225
	v_mul_f32_e32 v227, 0.5, v51
	v_mfma_f32_16x16x4_f32 v[72:75], v43, v172, v[72:75]
	v_add_f32_e32 v226, 1.0, v226
	v_rcp_f32_e32 v226, v226
	v_mfma_f32_16x16x4_f32 v[76:79], v43, v173, v[76:79]
	v_fma_f32 v226, v226, -2.0, 1.0
	v_fma_f32 v51, v227, v226, v227
	v_mfma_f32_16x16x4_f32 v[64:67], v44, v174, v[64:67]
	v_mul_f32_e32 v224, v52, v52
	v_mul_f32_e32 v224, v224, v52
	v_fma_f32 v225, s16, v224, v52
	v_mfma_f32_16x16x4_f32 v[68:71], v44, v175, v[68:71]
	v_mul_f32_e32 v225, s18, v225
	v_exp_f32_e32 v226, v225
	v_mul_f32_e32 v227, 0.5, v52
	v_mfma_f32_16x16x4_f32 v[72:75], v44, v176, v[72:75]
	v_add_f32_e32 v226, 1.0, v226
	v_rcp_f32_e32 v226, v226
	v_mfma_f32_16x16x4_f32 v[76:79], v44, v177, v[76:79]
	v_fma_f32 v226, v226, -2.0, 1.0
	v_fma_f32 v52, v227, v226, v227
	v_mfma_f32_16x16x4_f32 v[64:67], v45, v178, v[64:67]
	v_mul_f32_e32 v224, v53, v53
	v_mul_f32_e32 v224, v224, v53
	v_fma_f32 v225, s16, v224, v53
	v_mfma_f32_16x16x4_f32 v[68:71], v45, v179, v[68:71]
	v_mul_f32_e32 v225, s18, v225
	v_exp_f32_e32 v226, v225
	v_mul_f32_e32 v227, 0.5, v53
	v_mfma_f32_16x16x4_f32 v[72:75], v45, v180, v[72:75]
	v_add_f32_e32 v226, 1.0, v226
	v_rcp_f32_e32 v226, v226
	v_mfma_f32_16x16x4_f32 v[76:79], v45, v181, v[76:79]
	v_fma_f32 v226, v226, -2.0, 1.0
	v_fma_f32 v53, v227, v226, v227
	v_mfma_f32_16x16x4_f32 v[64:67], v46, v182, v[64:67]
	v_mul_f32_e32 v224, v54, v54
	v_mul_f32_e32 v224, v224, v54
	v_fma_f32 v225, s16, v224, v54
	v_mfma_f32_16x16x4_f32 v[68:71], v46, v183, v[68:71]
	v_mul_f32_e32 v225, s18, v225
	v_exp_f32_e32 v226, v225
	v_mul_f32_e32 v227, 0.5, v54
	v_mfma_f32_16x16x4_f32 v[72:75], v46, v184, v[72:75]
	v_add_f32_e32 v226, 1.0, v226
	v_rcp_f32_e32 v226, v226
	v_mfma_f32_16x16x4_f32 v[76:79], v46, v185, v[76:79]
	v_fma_f32 v226, v226, -2.0, 1.0
	v_fma_f32 v54, v227, v226, v227
	v_mfma_f32_16x16x4_f32 v[64:67], v47, v220, v[64:67]
	v_mul_f32_e32 v224, v55, v55
	v_mul_f32_e32 v224, v224, v55
	v_fma_f32 v225, s16, v224, v55
	v_mfma_f32_16x16x4_f32 v[68:71], v47, v221, v[68:71]
	v_mul_f32_e32 v225, s18, v225
	v_exp_f32_e32 v226, v225
	v_mul_f32_e32 v227, 0.5, v55
	v_mfma_f32_16x16x4_f32 v[72:75], v47, v222, v[72:75]
	v_add_f32_e32 v226, 1.0, v226
	v_rcp_f32_e32 v226, v226
	v_mfma_f32_16x16x4_f32 v[76:79], v47, v223, v[76:79]
	v_fma_f32 v226, v226, -2.0, 1.0
	v_fma_f32 v55, v227, v226, v227
	s_waitcnt vmcnt(8)
	v_mfma_f32_16x16x4_f32 v[64:67], v48, v82, v[64:67]
	v_mul_f32_e32 v224, v56, v56
	v_mul_f32_e32 v224, v224, v56
	v_fma_f32 v225, s16, v224, v56
	v_mfma_f32_16x16x4_f32 v[68:71], v48, v83, v[68:71]
	v_mul_f32_e32 v225, s18, v225
	v_exp_f32_e32 v226, v225
	v_mul_f32_e32 v227, 0.5, v56
	v_mfma_f32_16x16x4_f32 v[72:75], v48, v84, v[72:75]
	v_add_f32_e32 v226, 1.0, v226
	v_rcp_f32_e32 v226, v226
	v_mfma_f32_16x16x4_f32 v[76:79], v48, v85, v[76:79]
	v_fma_f32 v226, v226, -2.0, 1.0
	v_fma_f32 v56, v227, v226, v227
	v_mfma_f32_16x16x4_f32 v[64:67], v49, v86, v[64:67]
	v_mul_f32_e32 v224, v57, v57
	v_mul_f32_e32 v224, v224, v57
	v_fma_f32 v225, s16, v224, v57
	v_mfma_f32_16x16x4_f32 v[68:71], v49, v87, v[68:71]
	v_mul_f32_e32 v225, s18, v225
	v_exp_f32_e32 v226, v225
	v_mul_f32_e32 v227, 0.5, v57
	v_mfma_f32_16x16x4_f32 v[72:75], v49, v88, v[72:75]
	v_add_f32_e32 v226, 1.0, v226
	v_rcp_f32_e32 v226, v226
	v_mfma_f32_16x16x4_f32 v[76:79], v49, v89, v[76:79]
	v_fma_f32 v226, v226, -2.0, 1.0
	v_fma_f32 v57, v227, v226, v227
	v_mfma_f32_16x16x4_f32 v[64:67], v50, v90, v[64:67]
	v_mul_f32_e32 v224, v58, v58
	v_mul_f32_e32 v224, v224, v58
	v_fma_f32 v225, s16, v224, v58
	v_mfma_f32_16x16x4_f32 v[68:71], v50, v91, v[68:71]
	v_mul_f32_e32 v225, s18, v225
	v_exp_f32_e32 v226, v225
	v_mul_f32_e32 v227, 0.5, v58
	v_mfma_f32_16x16x4_f32 v[72:75], v50, v92, v[72:75]
	v_add_f32_e32 v226, 1.0, v226
	v_rcp_f32_e32 v226, v226
	v_mfma_f32_16x16x4_f32 v[76:79], v50, v93, v[76:79]
; __device__ __forceinline__ unsigned pk2(float lo, float hi) { f32x2_t v = {lo, hi}; bf16x2_t b = __builtin_convertvector(v, bf16x2_t); return __builtin_bit_cast(unsigned, b); }
; __device__ __forceinline__ float wave_sum(float v) { v += __shfl_xor(v, 1); v += __shfl_xor(v, 2); v += __shfl_xor(v, 4); v += __shfl_xor(v, 8); v += __shfl_xor(v, 16); v += __shfl_xor(v, 32); return v; }
; __global__ void __launch_bounds__(512, 2) hybrid_fwd(Params P) {
;     ...
;                 const float* wp = cw2 + (size_t)kv * 256 * 64 + lane; float a = 0.f;
; #pragma unroll
;                 for (int k = 0; k < 256; ++k) { const float hk = __uint_as_float(__builtin_amdgcn_readlane(__float_as_uint(hv[k & 3]), k >> 2)); a = fmaf(hk, wp[k * 64], a); }
;                 if (kv == 0) { const float ss = wave_sum(a * a); float y = a * __builtin_amdgcn_rsqf(ss * (1.0f / 64.0f) + 1e-6f) * nkn[lane]; if (n == 511) y = 0.f;
;     ...
;                 else { if (n == 511) a = 0.f; VCT[((size_t)bg * 64 + lane) * 512 + n] = (bf16_t)(pk2(a, 0.f) & 0xffffu); } }
	v_fma_f32 v226, v226, -2.0, 1.0
	v_fma_f32 v58, v227, v226, v227
	v_mfma_f32_16x16x4_f32 v[64:67], v51, v94, v[64:67]
	v_mul_f32_e32 v224, v59, v59
	v_mul_f32_e32 v224, v224, v59
	v_fma_f32 v225, s16, v224, v59
	v_mfma_f32_16x16x4_f32 v[68:71], v51, v95, v[68:71]
	v_mul_f32_e32 v225, s18, v225
	v_exp_f32_e32 v226, v225
	v_mul_f32_e32 v227, 0.5, v59
	v_mfma_f32_16x16x4_f32 v[72:75], v51, v96, v[72:75]
	v_add_f32_e32 v226, 1.0, v226
	v_rcp_f32_e32 v226, v226
	v_mfma_f32_16x16x4_f32 v[76:79], v51, v97, v[76:79]
	v_fma_f32 v226, v226, -2.0, 1.0
	v_fma_f32 v59, v227, v226, v227
	v_mfma_f32_16x16x4_f32 v[64:67], v52, v98, v[64:67]
	v_mul_f32_e32 v224, v60, v60
	v_mul_f32_e32 v224, v224, v60
	v_fma_f32 v225, s16, v224, v60
	v_mfma_f32_16x16x4_f32 v[68:71], v52, v99, v[68:71]
	v_mul_f32_e32 v225, s18, v225
	v_exp_f32_e32 v226, v225
	v_mul_f32_e32 v227, 0.5, v60
	v_mfma_f32_16x16x4_f32 v[72:75], v52, v100, v[72:75]
	v_add_f32_e32 v226, 1.0, v226
	v_rcp_f32_e32 v226, v226
	v_mfma_f32_16x16x4_f32 v[76:79], v52, v101, v[76:79]
	v_fma_f32 v226, v226, -2.0, 1.0
	v_fma_f32 v60, v227, v226, v227
	v_mfma_f32_16x16x4_f32 v[64:67], v53, v102, v[64:67]
	v_mul_f32_e32 v224, v61, v61
	v_mul_f32_e32 v224, v224, v61
	v_fma_f32 v225, s16, v224, v61
	v_mfma_f32_16x16x4_f32 v[68:71], v53, v103, v[68:71]
	v_mul_f32_e32 v225, s18, v225
	v_exp_f32_e32 v226, v225
	v_mul_f32_e32 v227, 0.5, v61
	v_mfma_f32_16x16x4_f32 v[72:75], v53, v104, v[72:75]
	v_add_f32_e32 v226, 1.0, v226
	v_rcp_f32_e32 v226, v226
	v_mfma_f32_16x16x4_f32 v[76:79], v53, v105, v[76:79]
	v_fma_f32 v226, v226, -2.0, 1.0
	v_fma_f32 v61, v227, v226, v227
	v_mfma_f32_16x16x4_f32 v[64:67], v54, v106, v[64:67]
	v_mul_f32_e32 v224, v62, v62
	v_mul_f32_e32 v224, v224, v62
	v_fma_f32 v225, s16, v224, v62
	v_mfma_f32_16x16x4_f32 v[68:71], v54, v107, v[68:71]
	v_mul_f32_e32 v225, s18, v225
	v_exp_f32_e32 v226, v225
	v_mul_f32_e32 v227, 0.5, v62
	v_mfma_f32_16x16x4_f32 v[72:75], v54, v108, v[72:75]
	v_add_f32_e32 v226, 1.0, v226
	v_rcp_f32_e32 v226, v226
	v_mfma_f32_16x16x4_f32 v[76:79], v54, v109, v[76:79]
	v_fma_f32 v226, v226, -2.0, 1.0
	v_fma_f32 v62, v227, v226, v227
	v_mfma_f32_16x16x4_f32 v[64:67], v55, v110, v[64:67]
	v_mul_f32_e32 v224, v63, v63
	v_mul_f32_e32 v224, v224, v63
	v_fma_f32 v225, s16, v224, v63
	v_mfma_f32_16x16x4_f32 v[68:71], v55, v111, v[68:71]
	v_mul_f32_e32 v225, s18, v225
	v_exp_f32_e32 v226, v225
	v_mul_f32_e32 v227, 0.5, v63
	v_mfma_f32_16x16x4_f32 v[72:75], v55, v112, v[72:75]
	v_add_f32_e32 v226, 1.0, v226
	v_rcp_f32_e32 v226, v226
	v_mfma_f32_16x16x4_f32 v[76:79], v55, v113, v[76:79]
	v_fma_f32 v226, v226, -2.0, 1.0
	v_fma_f32 v63, v227, v226, v227
	s_waitcnt vmcnt(0)
	v_mfma_f32_16x16x4_f32 v[64:67], v56, v114, v[64:67]
	v_mfma_f32_16x16x4_f32 v[68:71], v56, v115, v[68:71]
	v_mfma_f32_16x16x4_f32 v[72:75], v56, v116, v[72:75]
	v_mfma_f32_16x16x4_f32 v[76:79], v56, v117, v[76:79]
	v_mfma_f32_16x16x4_f32 v[64:67], v57, v118, v[64:67]
	v_mfma_f32_16x16x4_f32 v[68:71], v57, v119, v[68:71]
	v_mfma_f32_16x16x4_f32 v[72:75], v57, v120, v[72:75]
	v_mfma_f32_16x16x4_f32 v[76:79], v57, v121, v[76:79]
	v_mfma_f32_16x16x4_f32 v[64:67], v58, v122, v[64:67]
	v_mfma_f32_16x16x4_f32 v[68:71], v58, v123, v[68:71]
	v_mfma_f32_16x16x4_f32 v[72:75], v58, v124, v[72:75]
	v_mfma_f32_16x16x4_f32 v[76:79], v58, v125, v[76:79]
	v_mfma_f32_16x16x4_f32 v[64:67], v59, v126, v[64:67]
	v_mfma_f32_16x16x4_f32 v[68:71], v59, v127, v[68:71]
	v_mfma_f32_16x16x4_f32 v[72:75], v59, v128, v[72:75]
	v_mfma_f32_16x16x4_f32 v[76:79], v59, v129, v[76:79]
	v_mfma_f32_16x16x4_f32 v[64:67], v60, v130, v[64:67]
	v_mfma_f32_16x16x4_f32 v[68:71], v60, v131, v[68:71]
	v_mfma_f32_16x16x4_f32 v[72:75], v60, v132, v[72:75]
	v_mfma_f32_16x16x4_f32 v[76:79], v60, v133, v[76:79]
	v_mfma_f32_16x16x4_f32 v[64:67], v61, v134, v[64:67]
	v_mfma_f32_16x16x4_f32 v[68:71], v61, v135, v[68:71]
	v_mfma_f32_16x16x4_f32 v[72:75], v61, v136, v[72:75]
	v_mfma_f32_16x16x4_f32 v[76:79], v61, v137, v[76:79]
	v_mfma_f32_16x16x4_f32 v[64:67], v62, v138, v[64:67]
	v_mfma_f32_16x16x4_f32 v[68:71], v62, v139, v[68:71]
	v_mfma_f32_16x16x4_f32 v[72:75], v62, v140, v[72:75]
	v_mfma_f32_16x16x4_f32 v[76:79], v62, v141, v[76:79]
	v_mfma_f32_16x16x4_f32 v[64:67], v63, v142, v[64:67]
	v_mfma_f32_16x16x4_f32 v[68:71], v63, v143, v[68:71]
	v_mfma_f32_16x16x4_f32 v[72:75], v63, v144, v[72:75]
	v_mfma_f32_16x16x4_f32 v[76:79], v63, v145, v[76:79]
	s_nop 7
	s_nop 7
	v_lshl_add_u32 v253, v246, 2, s8
	v_and_b32_e32 v253, 0x1ff, v253
	v_cmp_eq_u32_e32 vcc, 0x1fc, v253
	s_mov_b64 s[18:19], vcc
	s_cmp_lg_u32 s9, 0
	s_cbranch_scc1 .Lphd_v
; __device__ __forceinline__ unsigned pk2(float lo, float hi) { f32x2_t v = {lo, hi}; bf16x2_t b = __builtin_convertvector(v, bf16x2_t); return __builtin_bit_cast(unsigned, b); }
; __device__ __forceinline__ float wave_sum(float v) { v += __shfl_xor(v, 1); v += __shfl_xor(v, 2); v += __shfl_xor(v, 4); v += __shfl_xor(v, 8); v += __shfl_xor(v, 16); v += __shfl_xor(v, 32); return v; }
; __global__ void __launch_bounds__(512, 2) hybrid_fwd(Params P) {
;     ...
;                 if (kv == 0) { const float ss = wave_sum(a * a); float y = a * __builtin_amdgcn_rsqf(ss * (1.0f / 64.0f) + 1e-6f) * nkn[lane]; if (n == 511) y = 0.f;
;                     KC[((size_t)bg * 512 + n) * 64 + lane] = (bf16_t)(pk2(y, 0.f) & 0xffffu); }
	v_mul_f32_e32 v0, v64, v64
	v_mul_f32_e32 v1, v65, v65
	v_mul_f32_e32 v2, v66, v66
	v_mul_f32_e32 v3, v67, v67
	v_fmac_f32_e32 v0, v68, v68
	v_fmac_f32_e32 v1, v69, v69
	v_fmac_f32_e32 v2, v70, v70
	v_fmac_f32_e32 v3, v71, v71
	v_fmac_f32_e32 v0, v72, v72
	v_fmac_f32_e32 v1, v73, v73
	v_fmac_f32_e32 v2, v74, v74
	v_fmac_f32_e32 v3, v75, v75
	v_fmac_f32_e32 v0, v76, v76
	v_fmac_f32_e32 v1, v77, v77
	v_fmac_f32_e32 v2, v78, v78
	v_fmac_f32_e32 v3, v79, v79
	s_nop 1
	v_add_f32_dpp v4, v0, v0 row_ror:8 row_mask:0xf bank_mask:0xf
	v_add_f32_dpp v5, v1, v1 row_ror:8 row_mask:0xf bank_mask:0xf
	v_add_f32_dpp v6, v2, v2 row_ror:8 row_mask:0xf bank_mask:0xf
	v_add_f32_dpp v7, v3, v3 row_ror:8 row_mask:0xf bank_mask:0xf
	s_nop 1
	v_mov_b32_e32 v0, v4
	v_mov_b32_e32 v1, v5
	v_mov_b32_e32 v2, v6
	v_mov_b32_e32 v3, v7
	s_nop 1
	v_add_f32_dpp v4, v0, v0 row_ror:4 row_mask:0xf bank_mask:0xf
	v_add_f32_dpp v5, v1, v1 row_ror:4 row_mask:0xf bank_mask:0xf
	v_add_f32_dpp v6, v2, v2 row_ror:4 row_mask:0xf bank_mask:0xf
	v_add_f32_dpp v7, v3, v3 row_ror:4 row_mask:0xf bank_mask:0xf
	s_nop 1
	v_mov_b32_e32 v0, v4
	v_mov_b32_e32 v1, v5
	v_mov_b32_e32 v2, v6
	v_mov_b32_e32 v3, v7
	s_nop 1
	v_add_f32_dpp v4, v0, v0 row_ror:2 row_mask:0xf bank_mask:0xf
	v_add_f32_dpp v5, v1, v1 row_ror:2 row_mask:0xf bank_mask:0xf
	v_add_f32_dpp v6, v2, v2 row_ror:2 row_mask:0xf bank_mask:0xf
	v_add_f32_dpp v7, v3, v3 row_ror:2 row_mask:0xf bank_mask:0xf
	s_nop 1
	v_mov_b32_e32 v0, v4
	v_mov_b32_e32 v1, v5
	v_mov_b32_e32 v2, v6
	v_mov_b32_e32 v3, v7
	s_nop 1
	v_add_f32_dpp v4, v0, v0 row_ror:1 row_mask:0xf bank_mask:0xf
	v_add_f32_dpp v5, v1, v1 row_ror:1 row_mask:0xf bank_mask:0xf
	v_add_f32_dpp v6, v2, v2 row_ror:1 row_mask:0xf bank_mask:0xf
	v_add_f32_dpp v7, v3, v3 row_ror:1 row_mask:0xf bank_mask:0xf
	s_nop 1
	v_mov_b32_e32 v0, v4
	v_mov_b32_e32 v1, v5
	v_mov_b32_e32 v2, v6
	v_mov_b32_e32 v3, v7
	v_fmamk_f32 v0, v0, 0x3c800000, v147
	v_fmamk_f32 v1, v1, 0x3c800000, v147
	v_fmamk_f32 v2, v2, 0x3c800000, v147
	v_fmamk_f32 v3, v3, 0x3c800000, v147
	v_rsq_f32_e32 v0, v0
	v_rsq_f32_e32 v1, v1
	v_rsq_f32_e32 v2, v2
	v_rsq_f32_e32 v3, v3
	s_nop 0
	v_mul_f32_e32 v64, v64, v0
	v_mul_f32_e32 v65, v65, v1
	v_mul_f32_e32 v66, v66, v2
	v_mul_f32_e32 v67, v67, v3
	v_mul_f32_e32 v68, v68, v0
	v_mul_f32_e32 v69, v69, v1
	v_mul_f32_e32 v70, v70, v2
	v_mul_f32_e32 v71, v71, v3
	v_mul_f32_e32 v72, v72, v0
	v_mul_f32_e32 v73, v73, v1
	v_mul_f32_e32 v74, v74, v2
	v_mul_f32_e32 v75, v75, v3
	v_mul_f32_e32 v76, v76, v0
	v_mul_f32_e32 v77, v77, v1
	v_mul_f32_e32 v78, v78, v2
	v_mul_f32_e32 v79, v79, v3
	v_mul_f32_e32 v64, v64, v240
	v_mul_f32_e32 v65, v65, v240
	v_mul_f32_e32 v66, v66, v240
	v_mul_f32_e32 v67, v67, v240
	v_mul_f32_e32 v68, v68, v241
	v_mul_f32_e32 v69, v69, v241
	v_mul_f32_e32 v70, v70, v241
	v_mul_f32_e32 v71, v71, v241
	v_mul_f32_e32 v72, v72, v242
	v_mul_f32_e32 v73, v73, v242
	v_mul_f32_e32 v74, v74, v242
	v_mul_f32_e32 v75, v75, v242
	v_mul_f32_e32 v76, v76, v243
	v_mul_f32_e32 v77, v77, v243
	v_mul_f32_e32 v78, v78, v243
	v_mul_f32_e32 v79, v79, v243
	v_cndmask_b32_e64 v67, v67, 0, s[18:19]
	v_cndmask_b32_e64 v71, v71, 0, s[18:19]
	v_cndmask_b32_e64 v75, v75, 0, s[18:19]
	v_cndmask_b32_e64 v79, v79, 0, s[18:19]
	v_cvt_pk_bf16_f32 v8, v64, v68
	v_cvt_pk_bf16_f32 v9, v72, v76
	v_cvt_pk_bf16_f32 v10, v65, v69
	v_cvt_pk_bf16_f32 v11, v73, v77
	v_cvt_pk_bf16_f32 v12, v66, v70
	v_cvt_pk_bf16_f32 v13, v74, v78
	v_cvt_pk_bf16_f32 v14, v67, v71
	v_cvt_pk_bf16_f32 v15, v75, v79
	s_lshl_b32 s16, s8, 7
	s_add_u32 s16, s16, 0x2d00000
	s_add_u32 s12, s4, s16
	s_addc_u32 s13, s5, 0
	global_store_dwordx2 v251, v[8:9], s[12:13]
	global_store_dwordx2 v251, v[10:11], s[12:13] offset:128
	global_store_dwordx2 v251, v[12:13], s[12:13] offset:256
	global_store_dwordx2 v251, v[14:15], s[12:13] offset:384
	s_branch .LBB0_784
